# GEMM epilogue 16-byte stores marked nt (streaming)
# baseline (speedup 1.0000x reference)
.LBB0_828:
	s_cmp_eq_u32 s26, s43
	v_lshl_or_b32 v130, s26, 8, v225
	s_cselect_b64 s[26:27], -1, 0
	s_and_b64 s[26:27], s[12:13], s[26:27]
	v_mad_i64_i32 v[136:137], s[28:29], s41, v204, 0
	s_and_b64 s[26:27], s[16:17], s[26:27]
	v_ashrrev_i32_e32 v131, 31, v130
	v_lshl_add_u64 v[136:137], v[136:137], 1, s[14:15]
	s_and_b64 s[26:27], s[26:27], s[0:1]
	v_cvt_pk_bf16_f32 v142, v126, v127
	v_cvt_pk_bf16_f32 v143, v128, v129
	v_cvt_pk_bf16_f32 v144, v122, v123
	v_cvt_pk_bf16_f32 v145, v124, v125
	v_lshl_add_u64 v[136:137], v[130:131], 1, v[136:137]
	global_store_dwordx4 v[136:137], v[142:145], off nt
	s_and_saveexec_b64 s[28:29], s[26:27]
	s_cbranch_execz .LBB0_830
	v_lshl_add_u64 v[142:143], v[160:161], 0, v[206:207]
	global_store_dwordx4 v[142:143], v[126:129], off nt
	global_store_dwordx4 v[142:143], v[122:125], off offset:16 nt

.LBB0_846:
	v_mul_f32_e32 v116, 0x4b800000, v208
	v_cndmask_b32_e64 v116, v208, v116, s[8:9]
	v_rsq_f32_e32 v116, v116
	v_cvt_pk_bf16_f32 v118, v118, v119
	v_cvt_pk_bf16_f32 v119, v120, v121
	v_cvt_pk_bf16_f32 v120, v114, v115
	v_mul_f32_e32 v114, 0x45800000, v116
	v_cndmask_b32_e64 v116, v116, v114, s[8:9]
	v_cvt_pk_bf16_f32 v121, v122, v117
	s_and_b64 vcc, exec, s[6:7]
	v_mul_f32_e32 v110, v110, v116
	global_store_dwordx4 v[136:137], v[118:121], off offset:256 nt
	s_cbranch_vccnz .LBB0_848
	v_mul_f32_e32 v114, 0x3d372713, v110
	v_mul_f32_e32 v114, v110, v114
	v_fma_f32 v114, v110, v114, v110
	v_mul_f32_e32 v114, 0xbfcc422a, v114
	v_mul_f32_e32 v114, 0x3fb8aa3b, v114
	v_exp_f32_e32 v114, v114
	s_nop 0
	v_add_f32_e32 v114, 1.0, v114
	v_rcp_f32_e32 v114, v114
	s_nop 0
	v_mul_f32_e32 v110, v110, v114

.LBB0_862:
	v_mad_i64_i32 v[114:115], s[8:9], s41, v202, 0
	v_lshl_add_u64 v[114:115], v[114:115], 1, s[14:15]
	v_cvt_pk_bf16_f32 v118, v110, v111
	v_cvt_pk_bf16_f32 v119, v112, v113
	v_cvt_pk_bf16_f32 v120, v106, v107
	v_cvt_pk_bf16_f32 v121, v108, v109
	v_lshl_add_u64 v[114:115], v[130:131], 1, v[114:115]
	global_store_dwordx4 v[114:115], v[118:121], off nt
	s_and_saveexec_b64 s[8:9], s[26:27]
	s_cbranch_execz .LBB0_864
	v_lshl_add_u64 v[118:119], v[160:161], 0, v[200:201]
	global_store_dwordx4 v[118:119], v[110:113], off nt
	global_store_dwordx4 v[118:119], v[106:109], off offset:16 nt

.LBB0_880:
	s_waitcnt lgkmcnt(4)
	v_pk_add_f32 v[98:99], v[146:147], v[148:149]
	s_mov_b32 s8, 0x3a800000
	v_pk_fma_f32 v[98:99], v[98:99], s[8:9], v[240:241] op_sel_hi:[1,0,0]
	v_cvt_pk_bf16_f32 v102, v102, v103
	v_mul_f32_e32 v108, 0x4b800000, v99
	v_cmp_gt_f32_e32 vcc, s91, v99
	v_cmp_gt_f32_e64 s[8:9], s91, v98
	s_nop 0
	v_cndmask_b32_e32 v99, v99, v108, vcc
	v_rsq_f32_e32 v99, v99
	s_nop 0
	v_mul_f32_e32 v103, 0x45800000, v99
	v_cndmask_b32_e32 v99, v99, v103, vcc
	v_cvt_pk_bf16_f32 v103, v104, v105
	v_cvt_pk_bf16_f32 v104, v106, v107
	v_cvt_pk_bf16_f32 v105, v100, v101
	s_and_b64 vcc, exec, s[6:7]
	v_mul_f32_e32 v94, v94, v99
	global_store_dwordx4 v[114:115], v[102:105], off offset:256 nt
	s_cbranch_vccnz .LBB0_882
	v_mul_f32_e32 v100, 0x3d372713, v94
	v_mul_f32_e32 v100, v94, v100
	v_fma_f32 v100, v94, v100, v94
	v_mul_f32_e32 v100, 0xbfcc422a, v100
	v_mul_f32_e32 v100, 0x3fb8aa3b, v100
	v_exp_f32_e32 v100, v100
	s_nop 0
	v_add_f32_e32 v100, 1.0, v100
	v_rcp_f32_e32 v100, v100
	s_nop 0
	v_mul_f32_e32 v94, v94, v100

.LBB0_896:
	v_mad_i64_i32 v[100:101], s[28:29], s41, v198, 0
	v_lshl_add_u64 v[100:101], v[100:101], 1, s[14:15]
	v_cvt_pk_bf16_f32 v102, v94, v95
	v_cvt_pk_bf16_f32 v103, v96, v97
	v_cvt_pk_bf16_f32 v104, v90, v91
	v_cvt_pk_bf16_f32 v105, v92, v93
	v_lshl_add_u64 v[100:101], v[130:131], 1, v[100:101]
	global_store_dwordx4 v[100:101], v[102:105], off nt
	s_and_saveexec_b64 s[28:29], s[26:27]
	s_cbranch_execz .LBB0_898
	v_lshl_add_u64 v[102:103], v[160:161], 0, v[196:197]
	global_store_dwordx4 v[102:103], v[94:97], off nt
	global_store_dwordx4 v[102:103], v[90:93], off offset:16 nt

.LBB0_914:
	v_mul_f32_e32 v84, 0x4b800000, v98
	v_cndmask_b32_e64 v84, v98, v84, s[8:9]
	v_rsq_f32_e32 v84, v84
	v_cvt_pk_bf16_f32 v86, v86, v87
	v_cvt_pk_bf16_f32 v87, v88, v89
	v_cvt_pk_bf16_f32 v88, v82, v83
	v_mul_f32_e32 v82, 0x45800000, v84
	v_cndmask_b32_e64 v84, v84, v82, s[8:9]
	v_cvt_pk_bf16_f32 v89, v90, v85
	s_and_b64 vcc, exec, s[6:7]
	v_mul_f32_e32 v78, v78, v84
	global_store_dwordx4 v[100:101], v[86:89], off offset:256 nt
	s_cbranch_vccnz .LBB0_916
	v_mul_f32_e32 v82, 0x3d372713, v78
	v_mul_f32_e32 v82, v78, v82
	v_fma_f32 v82, v78, v82, v78
	v_mul_f32_e32 v82, 0xbfcc422a, v82
	v_mul_f32_e32 v82, 0x3fb8aa3b, v82
	v_exp_f32_e32 v82, v82
	s_nop 0
	v_add_f32_e32 v82, 1.0, v82
	v_rcp_f32_e32 v82, v82
	s_nop 0
	v_mul_f32_e32 v78, v78, v82

.LBB0_930:
	v_mad_i64_i32 v[82:83], s[8:9], s41, v194, 0
	v_lshl_add_u64 v[82:83], v[82:83], 1, s[14:15]
	v_cvt_pk_bf16_f32 v86, v78, v79
	v_cvt_pk_bf16_f32 v87, v80, v81
	v_cvt_pk_bf16_f32 v88, v74, v75
	v_cvt_pk_bf16_f32 v89, v76, v77
	v_lshl_add_u64 v[82:83], v[130:131], 1, v[82:83]
	global_store_dwordx4 v[82:83], v[86:89], off nt
	s_and_saveexec_b64 s[8:9], s[26:27]
	s_cbranch_execz .LBB0_932
	v_lshl_add_u64 v[86:87], v[160:161], 0, v[192:193]
	global_store_dwordx4 v[86:87], v[78:81], off nt
	global_store_dwordx4 v[86:87], v[74:77], off offset:16 nt

.LBB0_948:
	s_waitcnt lgkmcnt(2)
	v_pk_add_f32 v[66:67], v[138:139], v[140:141]
	s_mov_b32 s8, 0x3a800000
	v_pk_fma_f32 v[66:67], v[66:67], s[8:9], v[240:241] op_sel_hi:[1,0,0]
	v_cvt_pk_bf16_f32 v70, v70, v71
	v_mul_f32_e32 v76, 0x4b800000, v67
	v_cmp_gt_f32_e32 vcc, s91, v67
	v_cmp_gt_f32_e64 s[8:9], s91, v66
	s_nop 0
	v_cndmask_b32_e32 v67, v67, v76, vcc
	v_rsq_f32_e32 v67, v67
	s_nop 0
	v_mul_f32_e32 v71, 0x45800000, v67
	v_cndmask_b32_e32 v67, v67, v71, vcc
	v_cvt_pk_bf16_f32 v71, v72, v73
	v_cvt_pk_bf16_f32 v72, v74, v75
	v_cvt_pk_bf16_f32 v73, v68, v69
	s_and_b64 vcc, exec, s[6:7]
	v_mul_f32_e32 v62, v62, v67
	global_store_dwordx4 v[82:83], v[70:73], off offset:256 nt
	s_cbranch_vccnz .LBB0_950
	v_mul_f32_e32 v68, 0x3d372713, v62
	v_mul_f32_e32 v68, v62, v68
	v_fma_f32 v68, v62, v68, v62
	v_mul_f32_e32 v68, 0xbfcc422a, v68
	v_mul_f32_e32 v68, 0x3fb8aa3b, v68
	v_exp_f32_e32 v68, v68
	s_nop 0
	v_add_f32_e32 v68, 1.0, v68
	v_rcp_f32_e32 v68, v68
	s_nop 0
	v_mul_f32_e32 v62, v62, v68

.LBB0_964:
	v_mad_i64_i32 v[68:69], s[28:29], s41, v190, 0
	v_lshl_add_u64 v[68:69], v[68:69], 1, s[14:15]
	v_cvt_pk_bf16_f32 v70, v62, v63
	v_cvt_pk_bf16_f32 v71, v64, v65
	v_cvt_pk_bf16_f32 v72, v58, v59
	v_cvt_pk_bf16_f32 v73, v60, v61
	v_lshl_add_u64 v[68:69], v[130:131], 1, v[68:69]
	global_store_dwordx4 v[68:69], v[70:73], off nt
	s_and_saveexec_b64 s[28:29], s[26:27]
	s_cbranch_execz .LBB0_966
	v_lshl_add_u64 v[70:71], v[160:161], 0, v[188:189]
	global_store_dwordx4 v[70:71], v[62:65], off nt
	global_store_dwordx4 v[70:71], v[58:61], off offset:16 nt

.LBB0_982:
	v_mul_f32_e32 v52, 0x4b800000, v66
	v_cndmask_b32_e64 v52, v66, v52, s[8:9]
	v_rsq_f32_e32 v52, v52
	v_cvt_pk_bf16_f32 v54, v54, v55
	v_cvt_pk_bf16_f32 v55, v56, v57
	v_cvt_pk_bf16_f32 v56, v50, v51
	v_mul_f32_e32 v50, 0x45800000, v52
	v_cndmask_b32_e64 v52, v52, v50, s[8:9]
	v_cvt_pk_bf16_f32 v57, v58, v53
	s_and_b64 vcc, exec, s[6:7]
	v_mul_f32_e32 v46, v46, v52
	global_store_dwordx4 v[68:69], v[54:57], off offset:256 nt
	s_cbranch_vccnz .LBB0_984
	v_mul_f32_e32 v50, 0x3d372713, v46
	v_mul_f32_e32 v50, v46, v50
	v_fma_f32 v50, v46, v50, v46
	v_mul_f32_e32 v50, 0xbfcc422a, v50
	v_mul_f32_e32 v50, 0x3fb8aa3b, v50
	v_exp_f32_e32 v50, v50
	s_nop 0
	v_add_f32_e32 v50, 1.0, v50
	v_rcp_f32_e32 v50, v50
	s_nop 0
	v_mul_f32_e32 v46, v46, v50

.LBB0_998:
	v_mad_i64_i32 v[50:51], s[8:9], s41, v186, 0
	v_lshl_add_u64 v[50:51], v[50:51], 1, s[14:15]
	v_cvt_pk_bf16_f32 v54, v46, v47
	v_cvt_pk_bf16_f32 v55, v48, v49
	v_cvt_pk_bf16_f32 v56, v42, v43
	v_cvt_pk_bf16_f32 v57, v44, v45
	v_lshl_add_u64 v[50:51], v[130:131], 1, v[50:51]
	global_store_dwordx4 v[50:51], v[54:57], off nt
	s_and_saveexec_b64 s[8:9], s[26:27]
	s_cbranch_execz .LBB0_1000
	v_lshl_add_u64 v[54:55], v[160:161], 0, v[184:185]
	global_store_dwordx4 v[54:55], v[46:49], off nt
	global_store_dwordx4 v[54:55], v[42:45], off offset:16 nt

.LBB0_1016:
	s_waitcnt lgkmcnt(0)
	v_pk_add_f32 v[34:35], v[132:133], v[134:135]
	s_mov_b32 s8, 0x3a800000
	v_pk_fma_f32 v[34:35], v[34:35], s[8:9], v[240:241] op_sel_hi:[1,0,0]
	v_cvt_pk_bf16_f32 v38, v38, v39
	v_mul_f32_e32 v44, 0x4b800000, v35
	v_cmp_gt_f32_e32 vcc, s91, v35
	v_cmp_gt_f32_e64 s[8:9], s91, v34
	s_nop 0
	v_cndmask_b32_e32 v35, v35, v44, vcc
	v_rsq_f32_e32 v35, v35
	s_nop 0
	v_mul_f32_e32 v39, 0x45800000, v35
	v_cndmask_b32_e32 v35, v35, v39, vcc
	v_cvt_pk_bf16_f32 v39, v40, v41
	v_cvt_pk_bf16_f32 v40, v42, v43
	v_cvt_pk_bf16_f32 v41, v36, v37
	s_and_b64 vcc, exec, s[6:7]
	v_mul_f32_e32 v30, v30, v35
	global_store_dwordx4 v[50:51], v[38:41], off offset:256 nt
	s_cbranch_vccnz .LBB0_1018
	v_mul_f32_e32 v36, 0x3d372713, v30
	v_mul_f32_e32 v36, v30, v36
	v_fma_f32 v36, v30, v36, v30
	v_mul_f32_e32 v36, 0xbfcc422a, v36
	v_mul_f32_e32 v36, 0x3fb8aa3b, v36
	v_exp_f32_e32 v36, v36
	s_nop 0
	v_add_f32_e32 v36, 1.0, v36
	v_rcp_f32_e32 v36, v36
	s_nop 0
	v_mul_f32_e32 v30, v30, v36

.LBB0_1032:
	v_mad_i64_i32 v[36:37], s[28:29], s41, v182, 0
	v_lshl_add_u64 v[36:37], v[36:37], 1, s[14:15]
	v_cvt_pk_bf16_f32 v38, v30, v31
	v_cvt_pk_bf16_f32 v39, v32, v33
	v_cvt_pk_bf16_f32 v40, v26, v27
	v_cvt_pk_bf16_f32 v41, v28, v29
	v_lshl_add_u64 v[36:37], v[130:131], 1, v[36:37]
	global_store_dwordx4 v[36:37], v[38:41], off nt
	s_and_saveexec_b64 s[28:29], s[26:27]
	s_cbranch_execz .LBB0_1034
	v_lshl_add_u64 v[38:39], v[160:161], 0, v[180:181]
	global_store_dwordx4 v[38:39], v[30:33], off nt
	global_store_dwordx4 v[38:39], v[26:29], off offset:16 nt

.LBB0_1050:
	v_mul_f32_e32 v20, 0x4b800000, v34
	v_cndmask_b32_e64 v20, v34, v20, s[8:9]
	v_rsq_f32_e32 v20, v20
	v_cvt_pk_bf16_f32 v22, v22, v23
	v_cvt_pk_bf16_f32 v23, v24, v25
	v_cvt_pk_bf16_f32 v24, v18, v19
	v_mul_f32_e32 v18, 0x45800000, v20
	v_cndmask_b32_e64 v20, v20, v18, s[8:9]
	v_cvt_pk_bf16_f32 v25, v26, v21
	s_and_b64 vcc, exec, s[6:7]
	v_mul_f32_e32 v14, v14, v20
	global_store_dwordx4 v[36:37], v[22:25], off offset:256 nt
	s_cbranch_vccnz .LBB0_1052
	v_mul_f32_e32 v18, 0x3d372713, v14
	v_mul_f32_e32 v18, v14, v18
	v_fma_f32 v18, v14, v18, v14
	v_mul_f32_e32 v18, 0xbfcc422a, v18
	v_mul_f32_e32 v18, 0x3fb8aa3b, v18
	v_exp_f32_e32 v18, v18
	s_nop 0
	v_add_f32_e32 v18, 1.0, v18
	v_rcp_f32_e32 v18, v18
	s_nop 0
	v_mul_f32_e32 v14, v14, v18

.LBB0_1066:
	v_mad_i64_i32 v[18:19], s[8:9], s41, v178, 0
	v_lshl_add_u64 v[18:19], v[18:19], 1, s[14:15]
	v_cvt_pk_bf16_f32 v22, v14, v15
	v_cvt_pk_bf16_f32 v23, v16, v17
	v_cvt_pk_bf16_f32 v24, v10, v11
	v_cvt_pk_bf16_f32 v25, v12, v13
	v_lshl_add_u64 v[18:19], v[130:131], 1, v[18:19]
	global_store_dwordx4 v[18:19], v[22:25], off nt
	s_and_saveexec_b64 s[8:9], s[26:27]
	s_cbranch_execz .LBB0_1068
	v_lshl_add_u64 v[22:23], v[160:161], 0, v[176:177]
	global_store_dwordx4 v[22:23], v[14:17], off nt
	global_store_dwordx4 v[22:23], v[10:13], off offset:16 nt

.LBB0_1084:
	v_cvt_pk_bf16_f32 v6, v6, v7
	v_cvt_pk_bf16_f32 v7, v8, v9
	v_cvt_pk_bf16_f32 v8, v2, v3
	v_cvt_pk_bf16_f32 v9, v4, v5
	s_andn2_b64 vcc, exec, s[4:5]
	s_mov_b64 s[4:5], -1
	global_store_dwordx4 v[18:19], v[6:9], off offset:256 nt
	s_cbranch_vccnz .LBB0_801
	s_andn2_b64 vcc, exec, s[2:3]
	s_cbranch_vccnz .LBB0_800
	s_barrier
	s_branch .LBB0_800

.LBB0_1347:
	v_lshl_add_u32 v182, s46, 8, v196
	v_lshl_or_b32 v180, s45, 8, v198
	v_readlane_b32 s6, v254, 28
	v_ashrrev_i32_e32 v181, 31, v180
	v_readlane_b32 s7, v254, 29
	v_ashrrev_i32_e32 v183, 31, v182
	v_lshlrev_b64 v[122:123], 11, v[182:183]
	v_lshl_add_u64 v[178:179], v[180:181], 1, s[6:7]
	v_or_b32_e32 v188, 16, v182
	v_lshl_add_u64 v[122:123], v[178:179], 0, v[122:123]
	v_ashrrev_i32_e32 v189, 31, v188
	global_load_dwordx4 v[200:203], v[122:123], off
	global_load_dwordx4 v[154:157], v[122:123], off offset:256
	v_lshlrev_b64 v[122:123], 11, v[188:189]
	v_or_b32_e32 v186, 32, v182
	v_lshl_add_u64 v[122:123], v[178:179], 0, v[122:123]
	v_ashrrev_i32_e32 v187, 31, v186
	global_load_dwordx4 v[150:153], v[122:123], off
	global_load_dwordx4 v[146:149], v[122:123], off offset:256
	v_lshlrev_b64 v[122:123], 11, v[186:187]
	v_or_b32_e32 v184, 48, v182
	v_lshl_add_u64 v[122:123], v[178:179], 0, v[122:123]
	v_ashrrev_i32_e32 v185, 31, v184
	global_load_dwordx4 v[142:145], v[122:123], off
	global_load_dwordx4 v[138:141], v[122:123], off offset:256
	v_lshlrev_b64 v[122:123], 11, v[184:185]
	v_lshl_add_u64 v[122:123], v[178:179], 0, v[122:123]
	global_load_dwordx4 v[134:137], v[122:123], off
	s_nop 0
	global_load_dwordx4 v[122:125], v[122:123], off offset:256
	v_lshlrev_b64 v[192:193], 10, v[182:183]
	v_lshl_add_u64 v[190:191], v[192:193], 0, v[180:181]
	s_andn2_b64 vcc, exec, s[18:19]
	v_lshl_add_u64 v[194:195], v[190:191], 2, s[2:3]
	s_waitcnt vmcnt(0)
	v_lshlrev_b32_e32 v162, 16, v200
	v_and_b32_e32 v163, 0xffff0000, v200
	v_pk_fma_f32 v[130:131], v[158:159], v[130:131], v[162:163]
	v_lshlrev_b32_e32 v162, 16, v201
	v_and_b32_e32 v163, 0xffff0000, v201
	v_pk_fma_f32 v[132:133], v[158:159], v[132:133], v[162:163]
	v_lshlrev_b32_e32 v162, 16, v202
	v_and_b32_e32 v163, 0xffff0000, v202
	v_pk_fma_f32 v[126:127], v[158:159], v[126:127], v[162:163]
	v_lshlrev_b32_e32 v162, 16, v203
	v_and_b32_e32 v163, 0xffff0000, v203
	v_pk_fma_f32 v[128:129], v[158:159], v[128:129], v[162:163]
	v_cndmask_b32_e64 v162, 0, 1, s[18:19]
	v_cmp_ne_u32_e64 s[6:7], 1, v162
	s_cbranch_vccnz .LBB0_1414
	global_store_dwordx4 v[194:195], v[130:133], off nt
	global_store_dwordx4 v[194:195], v[126:129], off offset:16 nt
	s_cbranch_execnz .LBB0_1350
.LBB0_1349:
	v_cvt_pk_bf16_f32 v200, v130, v131
	v_cvt_pk_bf16_f32 v201, v132, v133
	v_cvt_pk_bf16_f32 v202, v126, v127
	v_cvt_pk_bf16_f32 v203, v128, v129
	v_lshl_add_u64 v[162:163], v[192:193], 1, v[178:179]
	global_store_dwordx4 v[162:163], v[200:203], off nt
.LBB0_1350:
	v_lshlrev_b32_e32 v162, 16, v154
	v_and_b32_e32 v163, 0xffff0000, v154
	v_lshlrev_b32_e32 v154, 16, v155
	v_and_b32_e32 v155, 0xffff0000, v155
	v_pk_fma_f32 v[120:121], v[158:159], v[120:121], v[154:155]
	v_lshlrev_b32_e32 v154, 16, v156
	v_and_b32_e32 v155, 0xffff0000, v156
	v_pk_fma_f32 v[114:115], v[158:159], v[114:115], v[154:155]
	v_lshlrev_b32_e32 v154, 16, v157
	v_and_b32_e32 v155, 0xffff0000, v157
	v_pk_fma_f32 v[118:119], v[158:159], v[118:119], v[162:163]
	s_and_b64 vcc, exec, s[6:7]
	v_pk_fma_f32 v[116:117], v[158:159], v[116:117], v[154:155]
	s_cbranch_vccnz .LBB0_1415
	global_store_dwordx4 v[194:195], v[118:121], off offset:512 nt
	global_store_dwordx4 v[194:195], v[114:117], off offset:528 nt
	s_cbranch_execnz .LBB0_1353
.LBB0_1352:
	v_lshlrev_b64 v[162:163], 1, v[190:191]
	v_readlane_b32 s24, v254, 28
	v_or_b32_e32 v162, 0x100, v162
	v_readlane_b32 s25, v254, 29
	v_cvt_pk_bf16_f32 v154, v118, v119
	v_cvt_pk_bf16_f32 v155, v120, v121
	v_cvt_pk_bf16_f32 v156, v114, v115
	v_cvt_pk_bf16_f32 v157, v116, v117
	v_lshl_add_u64 v[162:163], s[24:25], 0, v[162:163]
	global_store_dwordx4 v[162:163], v[154:157], off nt

.LBB0_1355:
	s_or_b64 exec, exec, s[26:27]
	v_lshlrev_b32_e32 v116, 16, v150
	v_and_b32_e32 v117, 0xffff0000, v150
	v_pk_fma_f32 v[110:111], v[158:159], v[110:111], v[116:117]
	v_lshlrev_b32_e32 v116, 16, v151
	v_and_b32_e32 v117, 0xffff0000, v151
	v_lshlrev_b64 v[118:119], 10, v[188:189]
	v_pk_fma_f32 v[112:113], v[158:159], v[112:113], v[116:117]
	v_lshlrev_b32_e32 v116, 16, v152
	v_and_b32_e32 v117, 0xffff0000, v152
	s_waitcnt lgkmcnt(0)
	v_lshl_add_u64 v[114:115], v[118:119], 0, v[180:181]
	v_pk_fma_f32 v[106:107], v[158:159], v[106:107], v[116:117]
	v_lshlrev_b32_e32 v116, 16, v153
	v_and_b32_e32 v117, 0xffff0000, v153
	v_pk_fma_f32 v[108:109], v[158:159], v[108:109], v[116:117]
	s_and_b64 vcc, exec, s[6:7]
	v_lshl_add_u64 v[116:117], v[114:115], 2, s[2:3]
	s_cbranch_vccnz .LBB0_1416
	global_store_dwordx4 v[116:117], v[110:113], off nt
	global_store_dwordx4 v[116:117], v[106:109], off offset:16 nt
	s_cbranch_execnz .LBB0_1358
.LBB0_1357:
	v_cvt_pk_bf16_f32 v126, v110, v111
	v_cvt_pk_bf16_f32 v127, v112, v113
	v_cvt_pk_bf16_f32 v128, v106, v107
	v_cvt_pk_bf16_f32 v129, v108, v109
	v_lshl_add_u64 v[118:119], v[118:119], 1, v[178:179]
	global_store_dwordx4 v[118:119], v[126:129], off nt
.LBB0_1358:
	v_lshlrev_b32_e32 v118, 16, v146
	v_and_b32_e32 v119, 0xffff0000, v146
	v_pk_fma_f32 v[102:103], v[158:159], v[102:103], v[118:119]
	v_lshlrev_b32_e32 v118, 16, v147
	v_and_b32_e32 v119, 0xffff0000, v147
	v_pk_fma_f32 v[104:105], v[158:159], v[104:105], v[118:119]
	v_lshlrev_b32_e32 v118, 16, v148
	v_and_b32_e32 v119, 0xffff0000, v148
	v_pk_fma_f32 v[98:99], v[158:159], v[98:99], v[118:119]
	v_lshlrev_b32_e32 v118, 16, v149
	v_and_b32_e32 v119, 0xffff0000, v149
	s_and_b64 vcc, exec, s[6:7]
	v_pk_fma_f32 v[100:101], v[158:159], v[100:101], v[118:119]
	s_cbranch_vccnz .LBB0_1417
	global_store_dwordx4 v[116:117], v[102:105], off offset:512 nt
	global_store_dwordx4 v[116:117], v[98:101], off offset:528 nt
	s_cbranch_execnz .LBB0_1361
.LBB0_1360:
	v_lshlrev_b64 v[118:119], 1, v[114:115]
	v_readlane_b32 s26, v254, 28
	v_or_b32_e32 v118, 0x100, v118
	v_readlane_b32 s27, v254, 29
	v_cvt_pk_bf16_f32 v114, v102, v103
	v_cvt_pk_bf16_f32 v115, v104, v105
	v_cvt_pk_bf16_f32 v116, v98, v99
	v_cvt_pk_bf16_f32 v117, v100, v101
	v_lshl_add_u64 v[118:119], s[26:27], 0, v[118:119]
	global_store_dwordx4 v[118:119], v[114:117], off nt

.LBB0_1363:
	s_or_b64 exec, exec, s[26:27]
	v_lshlrev_b32_e32 v100, 16, v142
	v_and_b32_e32 v101, 0xffff0000, v142
	v_pk_fma_f32 v[94:95], v[158:159], v[94:95], v[100:101]
	v_lshlrev_b32_e32 v100, 16, v143
	v_and_b32_e32 v101, 0xffff0000, v143
	v_lshlrev_b64 v[102:103], 10, v[186:187]
	v_pk_fma_f32 v[96:97], v[158:159], v[96:97], v[100:101]
	v_lshlrev_b32_e32 v100, 16, v144
	v_and_b32_e32 v101, 0xffff0000, v144
	s_waitcnt lgkmcnt(0)
	v_lshl_add_u64 v[98:99], v[102:103], 0, v[180:181]
	v_pk_fma_f32 v[90:91], v[158:159], v[90:91], v[100:101]
	v_lshlrev_b32_e32 v100, 16, v145
	v_and_b32_e32 v101, 0xffff0000, v145
	v_pk_fma_f32 v[92:93], v[158:159], v[92:93], v[100:101]
	s_and_b64 vcc, exec, s[6:7]
	v_lshl_add_u64 v[100:101], v[98:99], 2, s[2:3]
	s_cbranch_vccnz .LBB0_1418
	global_store_dwordx4 v[100:101], v[94:97], off nt
	global_store_dwordx4 v[100:101], v[90:93], off offset:16 nt
	s_cbranch_execnz .LBB0_1366
.LBB0_1365:
	v_cvt_pk_bf16_f32 v104, v94, v95
	v_cvt_pk_bf16_f32 v105, v96, v97
	v_cvt_pk_bf16_f32 v106, v90, v91
	v_cvt_pk_bf16_f32 v107, v92, v93
	v_lshl_add_u64 v[102:103], v[102:103], 1, v[178:179]
	global_store_dwordx4 v[102:103], v[104:107], off nt
.LBB0_1366:
	v_lshlrev_b32_e32 v102, 16, v138
	v_and_b32_e32 v103, 0xffff0000, v138
	v_pk_fma_f32 v[86:87], v[158:159], v[86:87], v[102:103]
	v_lshlrev_b32_e32 v102, 16, v139
	v_and_b32_e32 v103, 0xffff0000, v139
	v_pk_fma_f32 v[88:89], v[158:159], v[88:89], v[102:103]
	v_lshlrev_b32_e32 v102, 16, v140
	v_and_b32_e32 v103, 0xffff0000, v140
	v_pk_fma_f32 v[82:83], v[158:159], v[82:83], v[102:103]
	v_lshlrev_b32_e32 v102, 16, v141
	v_and_b32_e32 v103, 0xffff0000, v141
	s_and_b64 vcc, exec, s[6:7]
	v_pk_fma_f32 v[84:85], v[158:159], v[84:85], v[102:103]
	s_cbranch_vccnz .LBB0_1419
	global_store_dwordx4 v[100:101], v[86:89], off offset:512 nt
	global_store_dwordx4 v[100:101], v[82:85], off offset:528 nt
	s_cbranch_execnz .LBB0_1369
.LBB0_1368:
	v_lshlrev_b64 v[102:103], 1, v[98:99]
	v_readlane_b32 s26, v254, 28
	v_or_b32_e32 v102, 0x100, v102
	v_readlane_b32 s27, v254, 29
	v_cvt_pk_bf16_f32 v98, v86, v87
	v_cvt_pk_bf16_f32 v99, v88, v89
	v_cvt_pk_bf16_f32 v100, v82, v83
	v_cvt_pk_bf16_f32 v101, v84, v85
	v_lshl_add_u64 v[102:103], s[26:27], 0, v[102:103]
	global_store_dwordx4 v[102:103], v[98:101], off nt

.LBB0_1371:
	s_or_b64 exec, exec, s[26:27]
	v_lshlrev_b32_e32 v84, 16, v134
	v_and_b32_e32 v85, 0xffff0000, v134
	v_pk_fma_f32 v[78:79], v[158:159], v[78:79], v[84:85]
	v_lshlrev_b32_e32 v84, 16, v135
	v_and_b32_e32 v85, 0xffff0000, v135
	v_lshlrev_b64 v[86:87], 10, v[184:185]
	v_pk_fma_f32 v[80:81], v[158:159], v[80:81], v[84:85]
	v_lshlrev_b32_e32 v84, 16, v136
	v_and_b32_e32 v85, 0xffff0000, v136
	s_waitcnt lgkmcnt(0)
	v_lshl_add_u64 v[82:83], v[86:87], 0, v[180:181]
	v_pk_fma_f32 v[74:75], v[158:159], v[74:75], v[84:85]
	v_lshlrev_b32_e32 v84, 16, v137
	v_and_b32_e32 v85, 0xffff0000, v137
	v_pk_fma_f32 v[76:77], v[158:159], v[76:77], v[84:85]
	s_and_b64 vcc, exec, s[6:7]
	v_lshl_add_u64 v[84:85], v[82:83], 2, s[2:3]
	s_cbranch_vccnz .LBB0_1420
	global_store_dwordx4 v[84:85], v[78:81], off nt
	global_store_dwordx4 v[84:85], v[74:77], off offset:16 nt
	s_cbranch_execnz .LBB0_1374
.LBB0_1373:
	v_cvt_pk_bf16_f32 v88, v78, v79
	v_cvt_pk_bf16_f32 v89, v80, v81
	v_cvt_pk_bf16_f32 v90, v74, v75
	v_cvt_pk_bf16_f32 v91, v76, v77
	v_lshl_add_u64 v[86:87], v[86:87], 1, v[178:179]
	global_store_dwordx4 v[86:87], v[88:91], off nt
.LBB0_1374:
	v_lshlrev_b32_e32 v86, 16, v122
	v_and_b32_e32 v87, 0xffff0000, v122
	v_pk_fma_f32 v[70:71], v[158:159], v[70:71], v[86:87]
	v_lshlrev_b32_e32 v86, 16, v123
	v_and_b32_e32 v87, 0xffff0000, v123
	v_pk_fma_f32 v[72:73], v[158:159], v[72:73], v[86:87]
	v_lshlrev_b32_e32 v86, 16, v124
	v_and_b32_e32 v87, 0xffff0000, v124
	v_pk_fma_f32 v[66:67], v[158:159], v[66:67], v[86:87]
	v_lshlrev_b32_e32 v86, 16, v125
	v_and_b32_e32 v87, 0xffff0000, v125
	s_and_b64 vcc, exec, s[6:7]
	v_pk_fma_f32 v[68:69], v[158:159], v[68:69], v[86:87]
	s_cbranch_vccnz .LBB0_1421
	global_store_dwordx4 v[84:85], v[70:73], off offset:512 nt
	global_store_dwordx4 v[84:85], v[66:69], off offset:528 nt
	s_cbranch_execnz .LBB0_1377
.LBB0_1376:
	v_lshlrev_b64 v[86:87], 1, v[82:83]
	v_readlane_b32 s26, v254, 28
	v_or_b32_e32 v86, 0x100, v86
	v_readlane_b32 s27, v254, 29
	v_cvt_pk_bf16_f32 v82, v70, v71
	v_cvt_pk_bf16_f32 v83, v72, v73
	v_cvt_pk_bf16_f32 v84, v66, v67
	v_cvt_pk_bf16_f32 v85, v68, v69
	v_lshl_add_u64 v[86:87], s[26:27], 0, v[86:87]
	global_store_dwordx4 v[86:87], v[82:85], off nt

.LBB0_1379:
	s_or_b64 exec, exec, s[26:27]
	v_add_u32_e32 v100, 0x80, v182
	v_ashrrev_i32_e32 v101, 31, v100
	s_waitcnt lgkmcnt(0)
	v_lshlrev_b64 v[66:67], 11, v[100:101]
	v_add_u32_e32 v98, 0x90, v182
	v_lshl_add_u64 v[66:67], v[178:179], 0, v[66:67]
	v_ashrrev_i32_e32 v99, 31, v98
	global_load_dwordx4 v[106:109], v[66:67], off
	global_load_dwordx4 v[90:93], v[66:67], off offset:256
	v_lshlrev_b64 v[66:67], 11, v[98:99]
	v_add_u32_e32 v96, 0xa0, v182
	v_lshl_add_u64 v[66:67], v[178:179], 0, v[66:67]
	v_ashrrev_i32_e32 v97, 31, v96
	global_load_dwordx4 v[86:89], v[66:67], off
	global_load_dwordx4 v[82:85], v[66:67], off offset:256
	v_lshlrev_b64 v[66:67], 11, v[96:97]
	v_add_u32_e32 v94, 0xb0, v182
	v_lshl_add_u64 v[66:67], v[178:179], 0, v[66:67]
	v_ashrrev_i32_e32 v95, 31, v94
	global_load_dwordx4 v[78:81], v[66:67], off
	global_load_dwordx4 v[74:77], v[66:67], off offset:256
	v_lshlrev_b64 v[66:67], 11, v[94:95]
	v_lshl_add_u64 v[66:67], v[178:179], 0, v[66:67]
	global_load_dwordx4 v[70:73], v[66:67], off
	s_nop 0
	global_load_dwordx4 v[66:69], v[66:67], off offset:256
	v_lshlrev_b64 v[104:105], 10, v[100:101]
	v_lshl_add_u64 v[102:103], v[104:105], 0, v[180:181]
	s_and_b64 vcc, exec, s[6:7]
	s_waitcnt vmcnt(7)
	v_lshlrev_b32_e32 v110, 16, v106
	v_and_b32_e32 v111, 0xffff0000, v106
	v_lshlrev_b32_e32 v106, 16, v107
	v_and_b32_e32 v107, 0xffff0000, v107
	v_pk_fma_f32 v[64:65], v[158:159], v[64:65], v[106:107]
	v_lshlrev_b32_e32 v106, 16, v108
	v_and_b32_e32 v107, 0xffff0000, v108
	v_pk_fma_f32 v[58:59], v[158:159], v[58:59], v[106:107]
	v_lshlrev_b32_e32 v106, 16, v109
	v_and_b32_e32 v107, 0xffff0000, v109
	v_pk_fma_f32 v[62:63], v[158:159], v[62:63], v[110:111]
	v_pk_fma_f32 v[60:61], v[158:159], v[60:61], v[106:107]
	v_lshl_add_u64 v[106:107], v[102:103], 2, s[2:3]
	s_cbranch_vccnz .LBB0_1422
	global_store_dwordx4 v[106:107], v[62:65], off nt
	global_store_dwordx4 v[106:107], v[58:61], off offset:16 nt
	s_cbranch_execnz .LBB0_1382
.LBB0_1381:
	v_cvt_pk_bf16_f32 v108, v62, v63
	v_cvt_pk_bf16_f32 v109, v64, v65
	v_cvt_pk_bf16_f32 v110, v58, v59
	v_cvt_pk_bf16_f32 v111, v60, v61
	v_lshl_add_u64 v[104:105], v[104:105], 1, v[178:179]
	global_store_dwordx4 v[104:105], v[108:111], off nt
.LBB0_1382:
	s_waitcnt vmcnt(6)
	v_lshlrev_b32_e32 v104, 16, v90
	v_and_b32_e32 v105, 0xffff0000, v90
	v_lshlrev_b32_e32 v90, 16, v91
	v_and_b32_e32 v91, 0xffff0000, v91
	v_pk_fma_f32 v[56:57], v[158:159], v[56:57], v[90:91]
	v_lshlrev_b32_e32 v90, 16, v92
	v_and_b32_e32 v91, 0xffff0000, v92
	v_pk_fma_f32 v[50:51], v[158:159], v[50:51], v[90:91]
	v_lshlrev_b32_e32 v90, 16, v93
	v_and_b32_e32 v91, 0xffff0000, v93
	v_pk_fma_f32 v[54:55], v[158:159], v[54:55], v[104:105]
	s_and_b64 vcc, exec, s[6:7]
	v_pk_fma_f32 v[52:53], v[158:159], v[52:53], v[90:91]
	s_cbranch_vccnz .LBB0_1423
	global_store_dwordx4 v[106:107], v[54:57], off offset:512 nt
	global_store_dwordx4 v[106:107], v[50:53], off offset:528 nt
	s_cbranch_execnz .LBB0_1385
.LBB0_1384:
	v_lshlrev_b64 v[102:103], 1, v[102:103]
	v_readlane_b32 s26, v254, 28
	v_or_b32_e32 v102, 0x100, v102
	v_readlane_b32 s27, v254, 29
	v_cvt_pk_bf16_f32 v90, v54, v55
	v_cvt_pk_bf16_f32 v91, v56, v57
	v_cvt_pk_bf16_f32 v92, v50, v51
	v_cvt_pk_bf16_f32 v93, v52, v53
	v_lshl_add_u64 v[102:103], s[26:27], 0, v[102:103]
	global_store_dwordx4 v[102:103], v[90:93], off nt

.LBB0_1387:
	s_or_b64 exec, exec, s[26:27]
	s_waitcnt vmcnt(5)
	v_lshlrev_b32_e32 v52, 16, v86
	v_and_b32_e32 v53, 0xffff0000, v86
	v_pk_fma_f32 v[46:47], v[158:159], v[46:47], v[52:53]
	v_lshlrev_b32_e32 v52, 16, v87
	v_and_b32_e32 v53, 0xffff0000, v87
	v_lshlrev_b64 v[54:55], 10, v[98:99]
	v_pk_fma_f32 v[48:49], v[158:159], v[48:49], v[52:53]
	v_lshlrev_b32_e32 v52, 16, v88
	v_and_b32_e32 v53, 0xffff0000, v88
	s_waitcnt lgkmcnt(0)
	v_lshl_add_u64 v[50:51], v[54:55], 0, v[180:181]
	v_pk_fma_f32 v[42:43], v[158:159], v[42:43], v[52:53]
	v_lshlrev_b32_e32 v52, 16, v89
	v_and_b32_e32 v53, 0xffff0000, v89
	v_pk_fma_f32 v[44:45], v[158:159], v[44:45], v[52:53]
	s_and_b64 vcc, exec, s[6:7]
	v_lshl_add_u64 v[52:53], v[50:51], 2, s[2:3]
	s_cbranch_vccnz .LBB0_1424
	global_store_dwordx4 v[52:53], v[46:49], off nt
	global_store_dwordx4 v[52:53], v[42:45], off offset:16 nt
	s_cbranch_execnz .LBB0_1390
.LBB0_1389:
	v_cvt_pk_bf16_f32 v56, v46, v47
	v_cvt_pk_bf16_f32 v57, v48, v49
	v_cvt_pk_bf16_f32 v58, v42, v43
	v_cvt_pk_bf16_f32 v59, v44, v45
	v_lshl_add_u64 v[54:55], v[54:55], 1, v[178:179]
	global_store_dwordx4 v[54:55], v[56:59], off nt
.LBB0_1390:
	s_waitcnt vmcnt(4)
	v_lshlrev_b32_e32 v54, 16, v82
	v_and_b32_e32 v55, 0xffff0000, v82
	v_pk_fma_f32 v[38:39], v[158:159], v[38:39], v[54:55]
	v_lshlrev_b32_e32 v54, 16, v83
	v_and_b32_e32 v55, 0xffff0000, v83
	v_pk_fma_f32 v[40:41], v[158:159], v[40:41], v[54:55]
	v_lshlrev_b32_e32 v54, 16, v84
	v_and_b32_e32 v55, 0xffff0000, v84
	v_pk_fma_f32 v[34:35], v[158:159], v[34:35], v[54:55]
	v_lshlrev_b32_e32 v54, 16, v85
	v_and_b32_e32 v55, 0xffff0000, v85
	s_and_b64 vcc, exec, s[6:7]
	v_pk_fma_f32 v[36:37], v[158:159], v[36:37], v[54:55]
	s_cbranch_vccnz .LBB0_1425
	global_store_dwordx4 v[52:53], v[38:41], off offset:512 nt
	global_store_dwordx4 v[52:53], v[34:37], off offset:528 nt
	s_cbranch_execnz .LBB0_1393
.LBB0_1392:
	v_lshlrev_b64 v[54:55], 1, v[50:51]
	v_readlane_b32 s26, v254, 28
	v_or_b32_e32 v54, 0x100, v54
	v_readlane_b32 s27, v254, 29
	v_cvt_pk_bf16_f32 v50, v38, v39
	v_cvt_pk_bf16_f32 v51, v40, v41
	v_cvt_pk_bf16_f32 v52, v34, v35
	v_cvt_pk_bf16_f32 v53, v36, v37
	v_lshl_add_u64 v[54:55], s[26:27], 0, v[54:55]
	global_store_dwordx4 v[54:55], v[50:53], off nt

.LBB0_1395:
	s_or_b64 exec, exec, s[26:27]
	s_waitcnt vmcnt(3)
	v_lshlrev_b32_e32 v36, 16, v78
	v_and_b32_e32 v37, 0xffff0000, v78
	v_pk_fma_f32 v[30:31], v[158:159], v[30:31], v[36:37]
	v_lshlrev_b32_e32 v36, 16, v79
	v_and_b32_e32 v37, 0xffff0000, v79
	v_lshlrev_b64 v[38:39], 10, v[96:97]
	v_pk_fma_f32 v[32:33], v[158:159], v[32:33], v[36:37]
	v_lshlrev_b32_e32 v36, 16, v80
	v_and_b32_e32 v37, 0xffff0000, v80
	s_waitcnt lgkmcnt(0)
	v_lshl_add_u64 v[34:35], v[38:39], 0, v[180:181]
	v_pk_fma_f32 v[26:27], v[158:159], v[26:27], v[36:37]
	v_lshlrev_b32_e32 v36, 16, v81
	v_and_b32_e32 v37, 0xffff0000, v81
	v_pk_fma_f32 v[28:29], v[158:159], v[28:29], v[36:37]
	s_and_b64 vcc, exec, s[6:7]
	v_lshl_add_u64 v[36:37], v[34:35], 2, s[2:3]
	s_cbranch_vccnz .LBB0_1426
	global_store_dwordx4 v[36:37], v[30:33], off nt
	global_store_dwordx4 v[36:37], v[26:29], off offset:16 nt
	s_cbranch_execnz .LBB0_1398
.LBB0_1397:
	v_cvt_pk_bf16_f32 v40, v30, v31
	v_cvt_pk_bf16_f32 v41, v32, v33
	v_cvt_pk_bf16_f32 v42, v26, v27
	v_cvt_pk_bf16_f32 v43, v28, v29
	v_lshl_add_u64 v[38:39], v[38:39], 1, v[178:179]
	global_store_dwordx4 v[38:39], v[40:43], off nt
.LBB0_1398:
	s_waitcnt vmcnt(2)
	v_lshlrev_b32_e32 v38, 16, v74
	v_and_b32_e32 v39, 0xffff0000, v74
	v_pk_fma_f32 v[22:23], v[158:159], v[22:23], v[38:39]
	v_lshlrev_b32_e32 v38, 16, v75
	v_and_b32_e32 v39, 0xffff0000, v75
	v_pk_fma_f32 v[24:25], v[158:159], v[24:25], v[38:39]
	v_lshlrev_b32_e32 v38, 16, v76
	v_and_b32_e32 v39, 0xffff0000, v76
	v_pk_fma_f32 v[18:19], v[158:159], v[18:19], v[38:39]
	v_lshlrev_b32_e32 v38, 16, v77
	v_and_b32_e32 v39, 0xffff0000, v77
	s_and_b64 vcc, exec, s[6:7]
	v_pk_fma_f32 v[20:21], v[158:159], v[20:21], v[38:39]
	s_cbranch_vccnz .LBB0_1427
	global_store_dwordx4 v[36:37], v[22:25], off offset:512 nt
	global_store_dwordx4 v[36:37], v[18:21], off offset:528 nt
	s_cbranch_execnz .LBB0_1401
.LBB0_1400:
	v_lshlrev_b64 v[38:39], 1, v[34:35]
	v_readlane_b32 s26, v254, 28
	v_or_b32_e32 v38, 0x100, v38
	v_readlane_b32 s27, v254, 29
	v_cvt_pk_bf16_f32 v34, v22, v23
	v_cvt_pk_bf16_f32 v35, v24, v25
	v_cvt_pk_bf16_f32 v36, v18, v19
	v_cvt_pk_bf16_f32 v37, v20, v21
	v_lshl_add_u64 v[38:39], s[26:27], 0, v[38:39]
	global_store_dwordx4 v[38:39], v[34:37], off nt

.LBB0_1403:
	s_or_b64 exec, exec, s[26:27]
	s_waitcnt vmcnt(1)
	v_lshlrev_b32_e32 v20, 16, v70
	v_and_b32_e32 v21, 0xffff0000, v70
	v_pk_fma_f32 v[14:15], v[158:159], v[14:15], v[20:21]
	v_lshlrev_b32_e32 v20, 16, v71
	v_and_b32_e32 v21, 0xffff0000, v71
	v_lshlrev_b64 v[22:23], 10, v[94:95]
	v_pk_fma_f32 v[16:17], v[158:159], v[16:17], v[20:21]
	v_lshlrev_b32_e32 v20, 16, v72
	v_and_b32_e32 v21, 0xffff0000, v72
	s_waitcnt lgkmcnt(0)
	v_lshl_add_u64 v[18:19], v[22:23], 0, v[180:181]
	v_pk_fma_f32 v[10:11], v[158:159], v[10:11], v[20:21]
	v_lshlrev_b32_e32 v20, 16, v73
	v_and_b32_e32 v21, 0xffff0000, v73
	v_pk_fma_f32 v[12:13], v[158:159], v[12:13], v[20:21]
	s_and_b64 vcc, exec, s[6:7]
	v_lshl_add_u64 v[20:21], v[18:19], 2, s[2:3]
	s_cbranch_vccnz .LBB0_1428
	global_store_dwordx4 v[20:21], v[14:17], off nt
	global_store_dwordx4 v[20:21], v[10:13], off offset:16 nt
	s_cbranch_execnz .LBB0_1406
.LBB0_1405:
	v_cvt_pk_bf16_f32 v24, v14, v15
	v_cvt_pk_bf16_f32 v25, v16, v17
	v_cvt_pk_bf16_f32 v26, v10, v11
	v_cvt_pk_bf16_f32 v27, v12, v13
	v_lshl_add_u64 v[22:23], v[22:23], 1, v[178:179]
	global_store_dwordx4 v[22:23], v[24:27], off nt
.LBB0_1406:
	s_waitcnt vmcnt(0)
	v_lshlrev_b32_e32 v22, 16, v66
	v_and_b32_e32 v23, 0xffff0000, v66
	v_pk_fma_f32 v[6:7], v[158:159], v[6:7], v[22:23]
	v_lshlrev_b32_e32 v22, 16, v67
	v_and_b32_e32 v23, 0xffff0000, v67
	v_pk_fma_f32 v[8:9], v[158:159], v[8:9], v[22:23]
	v_lshlrev_b32_e32 v22, 16, v68
	v_and_b32_e32 v23, 0xffff0000, v68
	v_pk_fma_f32 v[2:3], v[158:159], v[2:3], v[22:23]
	v_lshlrev_b32_e32 v22, 16, v69
	v_and_b32_e32 v23, 0xffff0000, v69
	s_and_b64 vcc, exec, s[6:7]
	v_pk_fma_f32 v[4:5], v[158:159], v[4:5], v[22:23]
	s_cbranch_vccnz .LBB0_1429
	global_store_dwordx4 v[20:21], v[6:9], off offset:512 nt
	global_store_dwordx4 v[20:21], v[2:5], off offset:528 nt
	s_cbranch_execnz .LBB0_1409
.LBB0_1408:
	v_lshlrev_b64 v[22:23], 1, v[18:19]
	v_readlane_b32 s6, v254, 28
	v_or_b32_e32 v22, 0x100, v22
	v_readlane_b32 s7, v254, 29
	v_cvt_pk_bf16_f32 v18, v6, v7
	v_cvt_pk_bf16_f32 v19, v8, v9
	v_cvt_pk_bf16_f32 v20, v2, v3
	v_cvt_pk_bf16_f32 v21, v4, v5
	v_lshl_add_u64 v[22:23], s[6:7], 0, v[22:23]
	global_store_dwordx4 v[22:23], v[18:21], off nt

.Lgu_rs_done:
	v_readlane_b32 s4, v254, 32
	v_readlane_b32 s5, v254, 33
	v_pk_mul_f32 v[126:127], v[126:127], v[194:195] op_sel_hi:[1,0]
	v_pk_mul_f32 v[122:123], v[122:123], v[194:195] op_sel_hi:[1,0]
	v_pk_mul_f32 v[124:125], v[124:125], v[194:195] op_sel_hi:[1,0]
	v_pk_mul_f32 v[118:119], v[118:119], v[194:195] op_sel_hi:[1,0]
	v_pk_mul_f32 v[114:115], v[114:115], v[194:195] op_sel_hi:[1,0]
	v_pk_mul_f32 v[116:117], v[116:117], v[194:195] op_sel_hi:[1,0]
	v_mul_f32_e32 v131, 0xbfb8aa3b, v126
	v_exp_f32_e32 v131, v131
	v_pk_mul_f32 v[110:111], v[110:111], v[192:193] op_sel_hi:[1,0]
	v_pk_mul_f32 v[106:107], v[106:107], v[192:193] op_sel_hi:[1,0]
	v_pk_mul_f32 v[108:109], v[108:109], v[192:193] op_sel_hi:[1,0]
	v_add_f32_e32 v131, 1.0, v131
	v_rcp_f32_e32 v134, v131
	v_mul_f32_e32 v131, 0xbfb8aa3b, v127
	v_exp_f32_e32 v131, v131
	v_pk_mul_f32 v[102:103], v[102:103], v[192:193] op_sel_hi:[1,0]
	v_pk_mul_f32 v[98:99], v[98:99], v[192:193] op_sel_hi:[1,0]
	v_pk_mul_f32 v[100:101], v[100:101], v[192:193] op_sel_hi:[1,0]
	v_add_f32_e32 v131, 1.0, v131
	v_rcp_f32_e32 v135, v131
	v_pk_mul_f32 v[94:95], v[94:95], v[148:149] op_sel_hi:[1,0]
	v_pk_mul_f32 v[90:91], v[90:91], v[148:149] op_sel_hi:[1,0]
	v_pk_mul_f32 v[92:93], v[92:93], v[148:149] op_sel_hi:[1,0]
	v_pk_mul_f32 v[126:127], v[126:127], v[134:135]
	v_pk_mul_f32 v[86:87], v[86:87], v[148:149] op_sel_hi:[1,0]
	v_pk_mul_f32 v[122:123], v[122:123], v[126:127]
	v_pk_mul_f32 v[126:127], v[128:129], v[194:195] op_sel_hi:[1,0]
	v_pk_mul_f32 v[82:83], v[82:83], v[148:149] op_sel_hi:[1,0]
	v_mul_f32_e32 v128, 0xbfb8aa3b, v126
	v_mul_f32_e32 v129, 0xbfb8aa3b, v127
	v_exp_f32_e32 v128, v128
	v_exp_f32_e32 v129, v129
	v_pk_mul_f32 v[84:85], v[84:85], v[148:149] op_sel_hi:[1,0]
	v_pk_mul_f32 v[78:79], v[78:79], v[146:147] op_sel_hi:[1,0]
	v_add_f32_e32 v128, 1.0, v128
	v_add_f32_e32 v129, 1.0, v129
	v_rcp_f32_e32 v128, v128
	v_rcp_f32_e32 v129, v129
	v_pk_mul_f32 v[74:75], v[74:75], v[146:147] op_sel_hi:[1,0]
	v_pk_mul_f32 v[76:77], v[76:77], v[146:147] op_sel_hi:[1,0]
	v_pk_mul_f32 v[70:71], v[70:71], v[146:147] op_sel_hi:[1,0]
	v_pk_mul_f32 v[126:127], v[126:127], v[128:129]
	v_pk_mul_f32 v[66:67], v[66:67], v[146:147] op_sel_hi:[1,0]
	v_pk_mul_f32 v[124:125], v[124:125], v[126:127]
	v_mul_f32_e32 v126, 0xbfb8aa3b, v118
	v_mul_f32_e32 v127, 0xbfb8aa3b, v119
	v_exp_f32_e32 v126, v126
	v_exp_f32_e32 v127, v127
	v_pk_mul_f32 v[68:69], v[68:69], v[146:147] op_sel_hi:[1,0]
	v_pk_mul_f32 v[62:63], v[62:63], v[140:141] op_sel_hi:[1,0]
	v_add_f32_e32 v126, 1.0, v126
	v_add_f32_e32 v127, 1.0, v127
	v_rcp_f32_e32 v126, v126
	v_rcp_f32_e32 v127, v127
	v_pk_mul_f32 v[58:59], v[58:59], v[140:141] op_sel_hi:[1,0]
	v_pk_mul_f32 v[60:61], v[60:61], v[140:141] op_sel_hi:[1,0]
	v_pk_mul_f32 v[54:55], v[54:55], v[140:141] op_sel_hi:[1,0]
	v_pk_mul_f32 v[118:119], v[118:119], v[126:127]
	v_pk_mul_f32 v[50:51], v[50:51], v[140:141] op_sel_hi:[1,0]
	v_pk_mul_f32 v[114:115], v[114:115], v[118:119]
	v_pk_mul_f32 v[118:119], v[120:121], v[194:195] op_sel_hi:[1,0]
	v_pk_mul_f32 v[52:53], v[52:53], v[140:141] op_sel_hi:[1,0]
	v_mul_f32_e32 v120, 0xbfb8aa3b, v118
	v_mul_f32_e32 v121, 0xbfb8aa3b, v119
	v_exp_f32_e32 v120, v120
	v_exp_f32_e32 v121, v121
	v_pk_mul_f32 v[46:47], v[46:47], v[138:139] op_sel_hi:[1,0]
	v_pk_mul_f32 v[42:43], v[42:43], v[138:139] op_sel_hi:[1,0]
	v_add_f32_e32 v120, 1.0, v120
	v_add_f32_e32 v121, 1.0, v121
	v_rcp_f32_e32 v120, v120
	v_rcp_f32_e32 v121, v121
	v_pk_mul_f32 v[44:45], v[44:45], v[138:139] op_sel_hi:[1,0]
	v_pk_mul_f32 v[38:39], v[38:39], v[138:139] op_sel_hi:[1,0]
	v_pk_mul_f32 v[34:35], v[34:35], v[138:139] op_sel_hi:[1,0]
	v_pk_mul_f32 v[118:119], v[118:119], v[120:121]
	v_cvt_pk_bf16_f32 v120, v114, v115
	v_pk_mul_f32 v[116:117], v[116:117], v[118:119]
	v_mov_b64_e32 v[114:115], s[4:5]
	v_cvt_pk_bf16_f32 v118, v122, v123
	v_cvt_pk_bf16_f32 v121, v116, v117
	v_mad_i64_i32 v[122:123], s[4:5], v188, s9, v[114:115]
	v_lshlrev_b64 v[116:117], 1, v[190:191]
	v_cvt_pk_bf16_f32 v119, v124, v125
	v_lshl_add_u64 v[122:123], v[122:123], 0, v[116:117]
	global_store_dwordx4 v[122:123], v[118:121], off nt
	s_cmp_lg_u64 s[6:7], 0
	s_cbranch_scc0 .Lgu_nox0
	s_barrier
.Lgu_nox0:
	v_pk_mul_f32 v[36:37], v[36:37], v[138:139] op_sel_hi:[1,0]
	v_pk_mul_f32 v[30:31], v[30:31], v[132:133] op_sel_hi:[1,0]
	v_mul_f32_e32 v118, 0xbfb8aa3b, v110
	v_mul_f32_e32 v119, 0xbfb8aa3b, v111
	v_exp_f32_e32 v118, v118
	v_exp_f32_e32 v119, v119
	v_pk_mul_f32 v[26:27], v[26:27], v[132:133] op_sel_hi:[1,0]
	v_pk_mul_f32 v[28:29], v[28:29], v[132:133] op_sel_hi:[1,0]
	v_add_f32_e32 v118, 1.0, v118
	v_add_f32_e32 v119, 1.0, v119
	v_rcp_f32_e32 v118, v118
	v_rcp_f32_e32 v119, v119
	v_pk_mul_f32 v[22:23], v[22:23], v[132:133] op_sel_hi:[1,0]
	v_pk_mul_f32 v[18:19], v[18:19], v[132:133] op_sel_hi:[1,0]
	v_pk_mul_f32 v[20:21], v[20:21], v[132:133] op_sel_hi:[1,0]
	v_pk_mul_f32 v[110:111], v[110:111], v[118:119]
	v_pk_mul_f32 v[14:15], v[14:15], v[130:131] op_sel_hi:[1,0]
	v_pk_mul_f32 v[106:107], v[106:107], v[110:111]
	v_pk_mul_f32 v[110:111], v[112:113], v[192:193] op_sel_hi:[1,0]
	v_pk_mul_f32 v[10:11], v[10:11], v[130:131] op_sel_hi:[1,0]
	v_mul_f32_e32 v112, 0xbfb8aa3b, v110
	v_mul_f32_e32 v113, 0xbfb8aa3b, v111
	v_exp_f32_e32 v112, v112
	v_exp_f32_e32 v113, v113
	v_pk_mul_f32 v[12:13], v[12:13], v[130:131] op_sel_hi:[1,0]
	v_pk_mul_f32 v[6:7], v[6:7], v[130:131] op_sel_hi:[1,0]
	v_add_f32_e32 v112, 1.0, v112
	v_add_f32_e32 v113, 1.0, v113
	v_rcp_f32_e32 v112, v112
	v_rcp_f32_e32 v113, v113
	v_pk_mul_f32 v[2:3], v[2:3], v[130:131] op_sel_hi:[1,0]
	v_pk_mul_f32 v[4:5], v[4:5], v[130:131] op_sel_hi:[1,0]
	s_andn2_b64 vcc, exec, s[0:1]
	v_pk_mul_f32 v[110:111], v[110:111], v[112:113]
	s_nop 0
	v_pk_mul_f32 v[108:109], v[108:109], v[110:111]
	v_mul_f32_e32 v110, 0xbfb8aa3b, v102
	v_mul_f32_e32 v111, 0xbfb8aa3b, v103
	v_exp_f32_e32 v110, v110
	v_exp_f32_e32 v111, v111
	v_add_f32_e32 v110, 1.0, v110
	v_add_f32_e32 v111, 1.0, v111
	v_rcp_f32_e32 v110, v110
	v_rcp_f32_e32 v111, v111
	s_nop 0
	v_pk_mul_f32 v[102:103], v[102:103], v[110:111]
	s_nop 0
	v_pk_mul_f32 v[102:103], v[98:99], v[102:103]
	v_pk_mul_f32 v[98:99], v[104:105], v[192:193] op_sel_hi:[1,0]
	s_nop 0
	v_mul_f32_e32 v104, 0xbfb8aa3b, v98
	v_mul_f32_e32 v105, 0xbfb8aa3b, v99
	v_exp_f32_e32 v104, v104
	v_exp_f32_e32 v105, v105
	v_add_f32_e32 v104, 1.0, v104
	v_add_f32_e32 v105, 1.0, v105
	v_rcp_f32_e32 v104, v104
	v_rcp_f32_e32 v105, v105
	s_nop 0
	v_pk_mul_f32 v[98:99], v[98:99], v[104:105]
	s_nop 0
	v_pk_mul_f32 v[104:105], v[100:101], v[98:99]
	v_cvt_pk_bf16_f32 v100, v102, v103
	v_mad_i64_i32 v[102:103], s[4:5], v186, s9, v[114:115]
	v_cvt_pk_bf16_f32 v98, v106, v107
	v_cvt_pk_bf16_f32 v99, v108, v109
	v_cvt_pk_bf16_f32 v101, v104, v105
	v_lshl_add_u64 v[102:103], v[102:103], 0, v[116:117]
	global_store_dwordx4 v[102:103], v[98:101], off nt
	s_nop 1
	v_mul_f32_e32 v98, 0xbfb8aa3b, v94
	v_mul_f32_e32 v99, 0xbfb8aa3b, v95
	v_exp_f32_e32 v98, v98
	v_exp_f32_e32 v99, v99
	v_add_f32_e32 v98, 1.0, v98
	v_add_f32_e32 v99, 1.0, v99
	v_rcp_f32_e32 v98, v98
	v_rcp_f32_e32 v99, v99
	s_nop 0
	v_pk_mul_f32 v[94:95], v[94:95], v[98:99]
	s_nop 0
	v_pk_mul_f32 v[90:91], v[90:91], v[94:95]
	v_pk_mul_f32 v[94:95], v[96:97], v[148:149] op_sel_hi:[1,0]
	s_nop 0
	v_mul_f32_e32 v96, 0xbfb8aa3b, v94
	v_mul_f32_e32 v97, 0xbfb8aa3b, v95
	v_exp_f32_e32 v96, v96
	v_exp_f32_e32 v97, v97
	v_add_f32_e32 v96, 1.0, v96
	v_add_f32_e32 v97, 1.0, v97
	v_rcp_f32_e32 v96, v96
	v_rcp_f32_e32 v97, v97
	s_nop 0
	v_pk_mul_f32 v[94:95], v[94:95], v[96:97]
	s_nop 0
	v_pk_mul_f32 v[92:93], v[92:93], v[94:95]
	v_mul_f32_e32 v94, 0xbfb8aa3b, v86
	v_mul_f32_e32 v95, 0xbfb8aa3b, v87
	v_exp_f32_e32 v94, v94
	v_exp_f32_e32 v95, v95
	v_add_f32_e32 v94, 1.0, v94
	v_add_f32_e32 v95, 1.0, v95
	v_rcp_f32_e32 v94, v94
	v_rcp_f32_e32 v95, v95
	s_nop 0
	v_pk_mul_f32 v[86:87], v[86:87], v[94:95]
	s_nop 0
	v_pk_mul_f32 v[86:87], v[82:83], v[86:87]
	v_pk_mul_f32 v[82:83], v[88:89], v[148:149] op_sel_hi:[1,0]
	s_nop 0
	v_mul_f32_e32 v88, 0xbfb8aa3b, v82
	v_mul_f32_e32 v89, 0xbfb8aa3b, v83
	v_exp_f32_e32 v88, v88
	v_exp_f32_e32 v89, v89
	v_add_f32_e32 v88, 1.0, v88
	v_add_f32_e32 v89, 1.0, v89
	v_rcp_f32_e32 v88, v88
	v_rcp_f32_e32 v89, v89
	s_nop 0
	v_pk_mul_f32 v[82:83], v[82:83], v[88:89]
	s_nop 0
	v_pk_mul_f32 v[88:89], v[84:85], v[82:83]
	v_cvt_pk_bf16_f32 v84, v86, v87
	v_mad_i64_i32 v[86:87], s[4:5], v184, s9, v[114:115]
	v_cvt_pk_bf16_f32 v82, v90, v91
	v_cvt_pk_bf16_f32 v83, v92, v93
	v_cvt_pk_bf16_f32 v85, v88, v89
	v_lshl_add_u64 v[86:87], v[86:87], 0, v[116:117]
	global_store_dwordx4 v[86:87], v[82:85], off nt
	s_nop 1
	v_mul_f32_e32 v82, 0xbfb8aa3b, v78
	v_mul_f32_e32 v83, 0xbfb8aa3b, v79
	v_exp_f32_e32 v82, v82
	v_exp_f32_e32 v83, v83
	v_add_f32_e32 v82, 1.0, v82
	v_add_f32_e32 v83, 1.0, v83
	v_rcp_f32_e32 v82, v82
	v_rcp_f32_e32 v83, v83
	s_nop 0
	v_pk_mul_f32 v[78:79], v[78:79], v[82:83]
	s_nop 0
	v_pk_mul_f32 v[74:75], v[74:75], v[78:79]
	v_pk_mul_f32 v[78:79], v[80:81], v[146:147] op_sel_hi:[1,0]
	s_nop 0
	v_mul_f32_e32 v80, 0xbfb8aa3b, v78
	v_mul_f32_e32 v81, 0xbfb8aa3b, v79
	v_exp_f32_e32 v80, v80
	v_exp_f32_e32 v81, v81
	v_add_f32_e32 v80, 1.0, v80
	v_add_f32_e32 v81, 1.0, v81
	v_rcp_f32_e32 v80, v80
	v_rcp_f32_e32 v81, v81
	s_nop 0
	v_pk_mul_f32 v[78:79], v[78:79], v[80:81]
	s_nop 0
	v_pk_mul_f32 v[76:77], v[76:77], v[78:79]
	v_mul_f32_e32 v78, 0xbfb8aa3b, v70
	v_mul_f32_e32 v79, 0xbfb8aa3b, v71
	v_exp_f32_e32 v78, v78
	v_exp_f32_e32 v79, v79
	v_add_f32_e32 v78, 1.0, v78
	v_add_f32_e32 v79, 1.0, v79
	v_rcp_f32_e32 v78, v78
	v_rcp_f32_e32 v79, v79
	s_nop 0
	v_pk_mul_f32 v[70:71], v[70:71], v[78:79]
	s_nop 0
	v_pk_mul_f32 v[70:71], v[66:67], v[70:71]
	v_pk_mul_f32 v[66:67], v[72:73], v[146:147] op_sel_hi:[1,0]
	s_nop 0
	v_mul_f32_e32 v72, 0xbfb8aa3b, v66
	v_mul_f32_e32 v73, 0xbfb8aa3b, v67
	v_exp_f32_e32 v72, v72
	v_exp_f32_e32 v73, v73
	v_add_f32_e32 v72, 1.0, v72
	v_add_f32_e32 v73, 1.0, v73
	v_rcp_f32_e32 v72, v72
	v_rcp_f32_e32 v73, v73
	s_nop 0
	v_pk_mul_f32 v[66:67], v[66:67], v[72:73]
	s_nop 0
	v_pk_mul_f32 v[72:73], v[68:69], v[66:67]
	v_cvt_pk_bf16_f32 v68, v70, v71
	v_mad_i64_i32 v[70:71], s[4:5], v182, s9, v[114:115]
	v_cvt_pk_bf16_f32 v66, v74, v75
	v_cvt_pk_bf16_f32 v67, v76, v77
	v_cvt_pk_bf16_f32 v69, v72, v73
	v_lshl_add_u64 v[70:71], v[70:71], 0, v[116:117]
	global_store_dwordx4 v[70:71], v[66:69], off nt
	s_nop 1
	v_mul_f32_e32 v66, 0xbfb8aa3b, v62
	v_mul_f32_e32 v67, 0xbfb8aa3b, v63
	v_exp_f32_e32 v66, v66
	v_exp_f32_e32 v67, v67
	v_add_f32_e32 v66, 1.0, v66
	v_add_f32_e32 v67, 1.0, v67
	v_rcp_f32_e32 v66, v66
	v_rcp_f32_e32 v67, v67
	s_nop 0
	v_pk_mul_f32 v[62:63], v[62:63], v[66:67]
	s_nop 0
	v_pk_mul_f32 v[58:59], v[58:59], v[62:63]
	v_pk_mul_f32 v[62:63], v[64:65], v[140:141] op_sel_hi:[1,0]
	s_nop 0
	v_mul_f32_e32 v64, 0xbfb8aa3b, v62
	v_mul_f32_e32 v65, 0xbfb8aa3b, v63
	v_exp_f32_e32 v64, v64
	v_exp_f32_e32 v65, v65
	v_add_f32_e32 v64, 1.0, v64
	v_add_f32_e32 v65, 1.0, v65
	v_rcp_f32_e32 v64, v64
	v_rcp_f32_e32 v65, v65
	s_nop 0
	v_pk_mul_f32 v[62:63], v[62:63], v[64:65]
	s_nop 0
	v_pk_mul_f32 v[60:61], v[60:61], v[62:63]
	v_mul_f32_e32 v62, 0xbfb8aa3b, v54
	v_mul_f32_e32 v63, 0xbfb8aa3b, v55
	v_exp_f32_e32 v62, v62
	v_exp_f32_e32 v63, v63
	v_add_f32_e32 v62, 1.0, v62
	v_add_f32_e32 v63, 1.0, v63
	v_rcp_f32_e32 v62, v62
	v_rcp_f32_e32 v63, v63
	s_nop 0
	v_pk_mul_f32 v[54:55], v[54:55], v[62:63]
	s_nop 0
	v_pk_mul_f32 v[54:55], v[50:51], v[54:55]
	v_pk_mul_f32 v[50:51], v[56:57], v[140:141] op_sel_hi:[1,0]
	s_nop 0
	v_mul_f32_e32 v56, 0xbfb8aa3b, v50
	v_mul_f32_e32 v57, 0xbfb8aa3b, v51
	v_exp_f32_e32 v56, v56
	v_exp_f32_e32 v57, v57
	v_add_f32_e32 v56, 1.0, v56
	v_add_f32_e32 v57, 1.0, v57
	v_rcp_f32_e32 v56, v56
	v_rcp_f32_e32 v57, v57
	s_nop 0
	v_pk_mul_f32 v[50:51], v[50:51], v[56:57]
	s_nop 0
	v_pk_mul_f32 v[56:57], v[52:53], v[50:51]
	v_cvt_pk_bf16_f32 v52, v54, v55
	v_mad_i64_i32 v[54:55], s[4:5], v180, s9, v[114:115]
	v_cvt_pk_bf16_f32 v50, v58, v59
	v_cvt_pk_bf16_f32 v51, v60, v61
	v_cvt_pk_bf16_f32 v53, v56, v57
	v_lshl_add_u64 v[54:55], v[54:55], 0, v[116:117]
	global_store_dwordx4 v[54:55], v[50:53], off nt
	s_nop 1
	v_mul_f32_e32 v50, 0xbfb8aa3b, v46
	v_mul_f32_e32 v51, 0xbfb8aa3b, v47
	v_exp_f32_e32 v50, v50
	v_exp_f32_e32 v51, v51
	v_add_f32_e32 v50, 1.0, v50
	v_add_f32_e32 v51, 1.0, v51
	v_rcp_f32_e32 v50, v50
	v_rcp_f32_e32 v51, v51
	s_nop 0
	v_pk_mul_f32 v[46:47], v[46:47], v[50:51]
	s_nop 0
	v_pk_mul_f32 v[42:43], v[42:43], v[46:47]
	v_pk_mul_f32 v[46:47], v[48:49], v[138:139] op_sel_hi:[1,0]
	s_nop 0
	v_mul_f32_e32 v48, 0xbfb8aa3b, v46
	v_mul_f32_e32 v49, 0xbfb8aa3b, v47
	v_exp_f32_e32 v48, v48
	v_exp_f32_e32 v49, v49
	v_add_f32_e32 v48, 1.0, v48
	v_add_f32_e32 v49, 1.0, v49
	v_rcp_f32_e32 v48, v48
	v_rcp_f32_e32 v49, v49
	s_nop 0
	v_pk_mul_f32 v[46:47], v[46:47], v[48:49]
	s_nop 0
	v_pk_mul_f32 v[44:45], v[44:45], v[46:47]
	v_mul_f32_e32 v46, 0xbfb8aa3b, v38
	v_mul_f32_e32 v47, 0xbfb8aa3b, v39
	v_exp_f32_e32 v46, v46
	v_exp_f32_e32 v47, v47
	v_add_f32_e32 v46, 1.0, v46
	v_add_f32_e32 v47, 1.0, v47
	v_rcp_f32_e32 v46, v46
	v_rcp_f32_e32 v47, v47
	s_nop 0
	v_pk_mul_f32 v[38:39], v[38:39], v[46:47]
	s_nop 0
	v_pk_mul_f32 v[38:39], v[34:35], v[38:39]
	v_pk_mul_f32 v[34:35], v[40:41], v[138:139] op_sel_hi:[1,0]
	s_nop 0
	v_mul_f32_e32 v40, 0xbfb8aa3b, v34
	v_mul_f32_e32 v41, 0xbfb8aa3b, v35
	v_exp_f32_e32 v40, v40
	v_exp_f32_e32 v41, v41
	v_add_f32_e32 v40, 1.0, v40
	v_add_f32_e32 v41, 1.0, v41
	v_rcp_f32_e32 v40, v40
	v_rcp_f32_e32 v41, v41
	s_nop 0
	v_pk_mul_f32 v[34:35], v[34:35], v[40:41]
	s_nop 0
	v_pk_mul_f32 v[40:41], v[36:37], v[34:35]
	v_cvt_pk_bf16_f32 v36, v38, v39
	v_mad_i64_i32 v[38:39], s[4:5], v178, s9, v[114:115]
	v_cvt_pk_bf16_f32 v34, v42, v43
	v_cvt_pk_bf16_f32 v35, v44, v45
	v_cvt_pk_bf16_f32 v37, v40, v41
	v_lshl_add_u64 v[38:39], v[38:39], 0, v[116:117]
	global_store_dwordx4 v[38:39], v[34:37], off nt
	s_nop 1
	v_mul_f32_e32 v34, 0xbfb8aa3b, v30
	v_mul_f32_e32 v35, 0xbfb8aa3b, v31
	v_exp_f32_e32 v34, v34
	v_exp_f32_e32 v35, v35
	v_add_f32_e32 v34, 1.0, v34
	v_add_f32_e32 v35, 1.0, v35
	v_rcp_f32_e32 v34, v34
	v_rcp_f32_e32 v35, v35
	s_nop 0
	v_pk_mul_f32 v[30:31], v[30:31], v[34:35]
	s_nop 0
	v_pk_mul_f32 v[26:27], v[26:27], v[30:31]
	v_pk_mul_f32 v[30:31], v[32:33], v[132:133] op_sel_hi:[1,0]
	s_nop 0
	v_mul_f32_e32 v32, 0xbfb8aa3b, v30
	v_mul_f32_e32 v33, 0xbfb8aa3b, v31
	v_exp_f32_e32 v32, v32
	v_exp_f32_e32 v33, v33
	v_add_f32_e32 v32, 1.0, v32
	v_add_f32_e32 v33, 1.0, v33
	v_rcp_f32_e32 v32, v32
	v_rcp_f32_e32 v33, v33
	s_nop 0
	v_pk_mul_f32 v[30:31], v[30:31], v[32:33]
	s_nop 0
	v_pk_mul_f32 v[28:29], v[28:29], v[30:31]
	v_mul_f32_e32 v30, 0xbfb8aa3b, v22
	v_mul_f32_e32 v31, 0xbfb8aa3b, v23
	v_exp_f32_e32 v30, v30
	v_exp_f32_e32 v31, v31
	v_add_f32_e32 v30, 1.0, v30
	v_add_f32_e32 v31, 1.0, v31
	v_rcp_f32_e32 v30, v30
	v_rcp_f32_e32 v31, v31
	s_nop 0
	v_pk_mul_f32 v[22:23], v[22:23], v[30:31]
	s_nop 0
	v_pk_mul_f32 v[22:23], v[18:19], v[22:23]
	v_pk_mul_f32 v[18:19], v[24:25], v[132:133] op_sel_hi:[1,0]
	s_nop 0
	v_mul_f32_e32 v24, 0xbfb8aa3b, v18
	v_mul_f32_e32 v25, 0xbfb8aa3b, v19
	v_exp_f32_e32 v24, v24
	v_exp_f32_e32 v25, v25
	v_add_f32_e32 v24, 1.0, v24
	v_add_f32_e32 v25, 1.0, v25
	v_rcp_f32_e32 v24, v24
	v_rcp_f32_e32 v25, v25
	s_nop 0
	v_pk_mul_f32 v[18:19], v[18:19], v[24:25]
	s_nop 0
	v_pk_mul_f32 v[24:25], v[20:21], v[18:19]
	v_cvt_pk_bf16_f32 v20, v22, v23
	v_mad_i64_i32 v[22:23], s[4:5], v176, s9, v[114:115]
	v_cvt_pk_bf16_f32 v18, v26, v27
	v_cvt_pk_bf16_f32 v19, v28, v29
	v_cvt_pk_bf16_f32 v21, v24, v25
	v_lshl_add_u64 v[22:23], v[22:23], 0, v[116:117]
	global_store_dwordx4 v[22:23], v[18:21], off nt
	s_nop 1
	v_mul_f32_e32 v18, 0xbfb8aa3b, v14
	v_mul_f32_e32 v19, 0xbfb8aa3b, v15
	v_exp_f32_e32 v18, v18
	v_exp_f32_e32 v19, v19
	v_add_f32_e32 v18, 1.0, v18
	v_add_f32_e32 v19, 1.0, v19
	v_rcp_f32_e32 v18, v18
	v_rcp_f32_e32 v19, v19
	s_nop 0
	v_pk_mul_f32 v[14:15], v[14:15], v[18:19]
	s_nop 0
	v_pk_mul_f32 v[10:11], v[10:11], v[14:15]
	v_pk_mul_f32 v[14:15], v[16:17], v[130:131] op_sel_hi:[1,0]
	s_nop 0
	v_mul_f32_e32 v16, 0xbfb8aa3b, v14
	v_mul_f32_e32 v17, 0xbfb8aa3b, v15
	v_exp_f32_e32 v16, v16
	v_exp_f32_e32 v17, v17
	v_add_f32_e32 v16, 1.0, v16
	v_add_f32_e32 v17, 1.0, v17
	v_rcp_f32_e32 v16, v16
	v_rcp_f32_e32 v17, v17
	s_nop 0
	v_pk_mul_f32 v[14:15], v[14:15], v[16:17]
	s_nop 0
	v_pk_mul_f32 v[12:13], v[12:13], v[14:15]
	v_mul_f32_e32 v14, 0xbfb8aa3b, v6
	v_mul_f32_e32 v15, 0xbfb8aa3b, v7
	v_exp_f32_e32 v14, v14
	v_exp_f32_e32 v15, v15
	v_add_f32_e32 v14, 1.0, v14
	v_add_f32_e32 v15, 1.0, v15
	v_rcp_f32_e32 v14, v14
	v_rcp_f32_e32 v15, v15
	s_nop 0
	v_pk_mul_f32 v[6:7], v[6:7], v[14:15]
	s_nop 0
	v_pk_mul_f32 v[6:7], v[2:3], v[6:7]
	v_pk_mul_f32 v[2:3], v[8:9], v[130:131] op_sel_hi:[1,0]
	s_nop 0
	v_mul_f32_e32 v8, 0xbfb8aa3b, v2
	v_mul_f32_e32 v9, 0xbfb8aa3b, v3
	v_exp_f32_e32 v8, v8
	v_exp_f32_e32 v9, v9
	v_add_f32_e32 v8, 1.0, v8
	v_add_f32_e32 v9, 1.0, v9
	v_rcp_f32_e32 v8, v8
	v_rcp_f32_e32 v9, v9
	s_nop 0
	v_pk_mul_f32 v[2:3], v[2:3], v[8:9]
	s_nop 0
	v_pk_mul_f32 v[8:9], v[4:5], v[2:3]
	v_cvt_pk_bf16_f32 v4, v6, v7
	v_mad_i64_i32 v[6:7], s[4:5], v174, s9, v[114:115]
	v_cvt_pk_bf16_f32 v2, v10, v11
	v_cvt_pk_bf16_f32 v3, v12, v13
	v_cvt_pk_bf16_f32 v5, v8, v9
	v_lshl_add_u64 v[6:7], v[6:7], 0, v[116:117]
	s_mov_b64 s[4:5], -1
	global_store_dwordx4 v[6:7], v[2:5], off nt
	s_cbranch_vccnz .LBB0_1438
	s_branch .LBB0_1437
